# v081 plus the same L2 warm-up in hg_pre
# baseline (speedup 1.0000x reference)
; __device__ __forceinline__ float bf2f(bfu h) { return __uint_as_float(((unsigned)h) << 16); }
; __device__ __forceinline__ int fragA_128(int r, int k) { return ((r >> 4) * 4 + (k >> 5)) * 512 + ((k >> 3) & 3) * 128 + (r & 15) * 8 + (k & 7); }
; __device__ void hg_pre_item(const Params& p, int L, int idx) {
;     ...
;   { const int d = tid & 127, rg = tid >> 7;
;     const float lb = misc[MF_LB + li * 512 + h * 128 + d];
;     bfu hqv[16], hfv[16], hiv[16];
;     _Pragma("unroll") for (int i = 0; i < 16; ++i) {
;       const bfu* pr = buf + (R0 + rg * 16 + i) * 4608 + 1536 + h * 128 + d;
;       hqv[i] = pr[0]; hfv[i] = pr[512]; hiv[i] = pr[1024];
;     ...
;   { const int d = tid & 127, rg = tid >> 7;
;     const float rown = (rg == 0) ? 0.f : bs[(16 * rg - 1) * 132 + d];
;     const float r1 = bs[15 * 132 + d], r2 = bs[31 * 132 + d], r3 = bs[47 * 132 + d];
;     for (int r = rg * 16; r < rg * 16 + 16; ++r) {
;       const float bb = bs[r * 132 + d];
;       const float qv = bf2f(qb[r * 136 + d]), kv = bf2f(kb[r * 136 + d]);
;       qt[r * 136 + d] = f2bf(qv * __builtin_amdgcn_exp2f(bb - rown));
;       { const int Lq = fragA_128(r, d); buf[(R0 + (Lq >> 7)) * 4608 + 1536 + h * 128 + (Lq & 127)] = f2bf(qv * __builtin_amdgcn_exp2f(bb)); }
;       if (rg < 1) kt[(0 + r) * 136 + d] = f2bf(kv * __builtin_amdgcn_exp2f(r1 - bb));
;       if (rg < 2) kt[(16 + r) * 136 + d] = f2bf(kv * __builtin_amdgcn_exp2f(r2 - bb));
;       if (rg < 3) kt[(48 + r) * 136 + d] = f2bf(kv * __builtin_amdgcn_exp2f(r3 - bb));
.LBB0_45:
	s_or_b64 exec, exec, s[0:1]
	v_cmp_lt_u32_e64 s[0:1], s24, v18
	v_mov_b32_e32 v9, 0
	v_lshlrev_b32_e32 v15, 2, v4
	s_waitcnt lgkmcnt(0)
	s_barrier
	v_mov_b32_e32 v240, s44
	v_lshrrev_b32_e32 v241, 8, v240
	v_add_u32_e32 v241, 1, v241
	v_min_u32_e32 v241, 7, v241
	v_and_b32_e32 v242, 63, v240
	v_lshlrev_b32_e32 v241, 12, v241
	v_lshl_or_b32 v241, v242, 6, v241
	v_mbcnt_lo_u32_b32 v243, -1, 0
	v_mbcnt_hi_u32_b32 v243, -1, v243
	v_or_b32_e32 v243, s33, v243
	v_lshrrev_b32_e32 v242, 3, v243
	v_and_b32_e32 v244, 7, v243
	v_min_u32_e32 v244, 5, v244
	v_add_u32_e32 v241, v241, v242
	v_mul_u32_u24_e32 v241, 0x2400, v241
	v_lshrrev_b32_e32 v245, 1, v244
	v_lshlrev_b32_e32 v245, 10, v245
	v_and_b32_e32 v244, 1, v244
	v_lshl_or_b32 v245, v244, 7, v245
	v_bfe_u32 v244, v240, 6, 2
	v_lshl_or_b32 v245, v244, 8, v245
	v_add_u32_e32 v245, 0xc00, v245
	v_add_u32_e32 v241, v241, v245
	global_load_dword v247, v241, s[16:17]
	s_and_saveexec_b64 s[12:13], s[0:1]
	v_add_u32_e32 v6, v20, v8
	s_movk_i32 s0, 0xfdf0
	v_add3_u32 v6, v6, v15, s0
	ds_read_b32 v9, v6
	s_or_b64 exec, exec, s[12:13]
	v_add_u32_e32 v6, 0xf0, v0
	ds_read2st64_b32 v[6:7], v6 offset0:30 offset1:63
	ds_read_b32 v11, v0 offset:24816
	v_lshlrev_b32_e32 v0, 4, v4
	s_movk_i32 s2, 0x1100
	v_and_b32_e32 v13, 0x180, v0
	v_mul_lo_u32 v0, v19, s2
	s_add_u32 s12, s16, s26
	v_lshl_or_b32 v0, v4, 1, v0
	v_lshrrev_b32_e32 v12, 5, v4
	v_and_b32_e32 v10, 7, v18
	v_cmp_gt_i32_e64 s[0:1], 1, v19
	v_cmp_gt_i32_e64 s[38:39], 2, v19
	v_cmp_gt_i32_e64 s[40:41], 3, v19
	s_addc_u32 s13, s17, 0
	v_lshlrev_b32_e32 v14, 7, v19
	v_add_u32_e32 v4, 0, v0
	v_add3_u32 v8, v8, v15, 0
	s_mov_b32 s2, 0
	s_branch .LBB0_49
